# attn_sw: static priority 2 for waves 4-7, per-group setprio toggles removed (induce MFMA/VALU stagger between SIMD wave pairs) + epilogue load batching + permlane row-max
# baseline (speedup 1.0000x reference)
; __device__ __forceinline__ void nsa_attn_sw(const Ctx& c, const bf16* Q, const bf16* T, const bf16* VT, const float* Gt, const float* NACC, float* NACC2, const unsigned long long* SMg, bf16* OUT) {
;     const int l15 = c.lane & 15, lg = c.lane >> 4, lane = c.lane;
;     for (int uu_ = c.vcu; uu_ < (PROBE == 21 ? 2048 : 1024); uu_ += c.G) { const int uu = uu_ & 1023;
;         NSA_UNIT_PROLOGUE
;         unsigned long long um = SMg[(size_t)bg * SEQ + t0 + lane];
; #pragma unroll
;         for (int o = 1; o < 64; o <<= 1) { const unsigned lo_ = __shfl_xor((unsigned)um, o), hi_ = __shfl_xor((unsigned)(um >> 32), o); um |= ((unsigned long long)hi_ << 32) | lo_; }
;         const unsigned long long umu = ((unsigned long long)__builtin_amdgcn_readfirstlane((unsigned)(um >> 32)) << 32) | (unsigned)__builtin_amdgcn_readfirstlane((unsigned)um);
;         f32x4 O[8][2]; float m[2], l[2]; const float invl[2] = {0.f, 0.f};
;         { fa::SelMask mk; mk.qb = qb; mk.tq[0] = tq[0]; mk.tq[1] = tq[1]; mk.sm[0] = SMg[(size_t)bg * SEQ + tq[0]]; mk.sm[1] = SMg[(size_t)bg * SEQ + tq[1]];
;           const unsigned long long tiles = umu & ((2ull << qb) - 1ull);
;           fa::Src src{T + 2 * NT_STRIDE + (size_t)bg * 4096 * 128, 128, VT + (size_t)bg * 128 * 4096, 4096};
;           m[0] = m[1] = -1e30f; l[0] = l[1] = 0.f;
; #pragma unroll
;           for (int dt = 0; dt < 8; ++dt) { O[dt][0] = (f32x4){0.f, 0.f, 0.f, 0.f}; O[dt][1] = (f32x4){0.f, 0.f, 0.f, 0.f}; }
;           fa::run<0>(c.lds, src, tiles, Qf, O, m, l, invl, mk, c.tid, c.wave, l15, lg);
.LBB0_2304:
	v_readlane_b32 s2, v253, 13
	s_cmp_lt_i32 s2, 22
	s_cselect_b64 s[12:13], -1, 0
	v_readlane_b32 s3, v253, 14
	s_and_b64 s[0:1], s[12:13], s[0:1]
	v_cndmask_b32_e64 v3, 0, 1, s[24:25]
	s_andn2_b64 vcc, exec, s[0:1]
	v_cmp_ne_u32_e64 s[2:3], 1, v3
	s_cbranch_vccnz .LBB0_2352
	s_and_b64 vcc, exec, s[2:3]
	s_cbranch_vccnz .LBB0_2352
	s_cmp_lt_u32 s97, 4
	s_cbranch_scc1 .Lprio_lo_sw
	s_setprio 2
.Lprio_lo_sw:
	v_mov_b32_e32 v5, 0
	v_mov_b32_e32 v3, v5
	v_lshl_add_u64 v[228:229], s[18:19], 0, v[2:3]
	v_mbcnt_lo_u32_b32 v3, -1, 0
	v_mbcnt_hi_u32_b32 v7, -1, v3
	v_lshrrev_b32_e32 v6, 4, v164
	v_and_b32_e32 v3, 64, v7
	v_lshlrev_b32_e32 v171, 3, v6
	v_add_u32_e32 v8, 64, v3
	v_lshlrev_b32_e32 v170, 2, v6
	v_xor_b32_e32 v6, 1, v7
	v_cmp_lt_i32_e32 vcc, v6, v8
	v_readlane_b32 s0, v253, 0
	v_readlane_b32 s1, v253, 1
	v_cndmask_b32_e32 v6, v7, v6, vcc
	v_lshlrev_b32_e32 v175, 2, v6
	v_xor_b32_e32 v6, 2, v7
	v_cmp_lt_i32_e32 vcc, v6, v8
	s_add_u32 s14, s0, 0x27400000
	v_and_b32_e32 v4, 15, v0
	v_cndmask_b32_e32 v6, v7, v6, vcc
	v_lshlrev_b32_e32 v177, 2, v6
	v_xor_b32_e32 v6, 4, v7
	v_cmp_lt_i32_e32 vcc, v6, v8
	s_addc_u32 s15, s1, 0
	v_mul_u32_u24_e32 v3, 0x110, v4
	v_cndmask_b32_e32 v6, v7, v6, vcc
	v_lshlrev_b32_e32 v206, 2, v6
	v_xor_b32_e32 v6, 8, v7
	v_cmp_lt_i32_e32 vcc, v6, v8
	v_mul_u32_u24_e32 v173, 0x90, v4
	v_lshl_or_b32 v4, s97, 5, v4
	v_cndmask_b32_e32 v6, v7, v6, vcc
	v_lshlrev_b32_e32 v207, 2, v6
	v_xor_b32_e32 v6, 16, v7
	v_cmp_lt_i32_e32 vcc, v6, v8
	s_add_u32 s21, s0, 0x1b400000
	v_lshrrev_b32_e32 v172, 2, v4
	v_cndmask_b32_e32 v6, v7, v6, vcc
	v_lshlrev_b32_e32 v208, 2, v6
	v_xor_b32_e32 v6, 32, v7
	v_cmp_lt_i32_e32 vcc, v6, v8
	v_lshlrev_b32_e32 v4, 3, v0
	s_addc_u32 s26, s1, 0
	v_cndmask_b32_e32 v6, v7, v6, vcc
	v_lshlrev_b32_e32 v209, 2, v6
	v_or_b32_e32 v6, 0x200, v0
	v_lshlrev_b32_e32 v7, 4, v0
	v_and_b32_e32 v174, 0x78, v4
	v_and_b32_e32 v176, 56, v4
	v_lshrrev_b32_e32 v4, 3, v0
	v_lshrrev_b32_e32 v211, 4, v6
	v_lshrrev_b32_e32 v6, 3, v6
	v_and_b32_e32 v212, 0xf0, v7
	v_and_b32_e32 v213, 0x70, v7
	s_add_u32 s27, s0, 0x1d400000
	v_add_u32_e32 v8, 0, v212
	v_add_u32_e32 v7, 0, v213
	v_mul_u32_u24_e32 v214, 0x110, v231
	v_mul_u32_u24_e32 v215, 0x90, v4
	v_mul_u32_u24_e32 v216, 0x110, v211
	v_mul_u32_u24_e32 v217, 0x90, v6
	v_and_b32_e32 v233, 3, v0
	s_mov_b32 s19, 0
	s_addc_u32 s28, s1, 0
	v_or_b32_e32 v210, 4, v172
	v_lshlrev_b32_e32 v178, 13, v4
	v_mov_b32_e32 v179, v5
	v_lshlrev_b32_e32 v180, 13, v6
	v_mov_b32_e32 v181, v5
	v_lshlrev_b32_e32 v251, 3, v164
	v_lshlrev_b32_e32 v252, 3, v172
	s_mov_b32 s29, 0xff800000
	s_mov_b32 s30, 0x3e0293ee
	s_mov_b32 s8, 0x3f803f80
	s_mov_b32 s20, 0x3e800000
	s_movk_i32 s31, 0xc0
	s_movk_i32 s34, 0x7fff
	s_mov_b32 s35, 0xffff0000
	v_add_u32_e32 v232, v8, v214
	v_add_u32_e32 v165, v7, v215
	v_add_u32_e32 v222, v8, v216
	v_add_u32_e32 v223, v7, v217
	v_mov_b32_e32 v224, 0xff800000
	v_readlane_b32 s36, v253, 12
	s_branch .LBB0_2309

; #define LAS __attribute__((address_space(3)))
; template <int MODE, class MaskF> ...
;     ...
;     const LAS unsigned char* kbase = buf + l15 * KS_STRIDE + lg * 16;
;     bf16x8 kf[2][2];
; #pragma unroll
;     for (int q = 0; q < 2; ++q) kf[0][q] = *(const LAS bf16x8*)(kbase + q * 16 * KS_STRIDE);
; #pragma unroll
;     for (int h = 0; h < 8; ++h) { const int ks = h >> 1, n0 = (h & 1) * 2;
;         if (h < 7) { const int ks1 = (h + 1) >> 1, n1 = ((h + 1) & 1) * 2;
; #pragma unroll
;             for (int q = 0; q < 2; ++q) kf[(h + 1) & 1][q] = *(const LAS bf16x8*)(kbase + (n1 + q) * 16 * KS_STRIDE + ks1 * 64); }
;         __builtin_amdgcn_sched_barrier(0);
;         __builtin_amdgcn_s_setprio(1);
; #pragma unroll
;         for (int q = 0; q < 2; ++q)
; #pragma unroll
;             for (int mi = 0; mi < 2; ++mi) S[n0 + q][mi] = __builtin_amdgcn_mfma_f32_16x16x32_bf16(kf[h & 1][q], Qf[mi][ks], S[n0 + q][mi], 0, 0, 0);
;         __builtin_amdgcn_s_setprio(0);
;         __builtin_amdgcn_sched_barrier(0);
;     }
;     const float NEG = -__builtin_inff();
;     float mx[2] = {NEG, NEG};
;     if (mf.need(kb)) {
; #pragma unroll
;         for (int nt = 0; nt < 4; ++nt)
; #pragma unroll
;             for (int mi = 0; mi < 2; ++mi)
; #pragma unroll
;                 for (int r = 0; r < 4; ++r) { const float sv = mf.valid(kb, 16 * nt + 4 * lg + r, mi) ? S[nt][mi][r] : NEG; S[nt][mi][r] = sv; mx[mi] = fmaxf(mx[mi], sv); }
;     } else {
; #pragma unroll
;         for (int nt = 0; nt < 4; ++nt)
; #pragma unroll
;             for (int mi = 0; mi < 2; ++mi)
; #pragma unroll
;                 for (int r = 0; r < 4; ++r) mx[mi] = fmaxf(mx[mi], S[nt][mi][r]);
; template <int MODE, class MaskF> ...
;     ...
;         const bool more = tiles != 0ull; int nkb = 0;
;         if (more) { nkb = __builtin_ctzll(tiles); tiles &= tiles - 1ull; }
;         bf16x8 Pf[2][2];
;         tile_qk<MODE>(lds + cur * BUF_BYTES, Qf, O, m, l, invl, kb, mf, (LAS float*)(lds + PS_OFF), wave, l15, lg, Pf, OL);
;         __builtin_amdgcn_sched_barrier(0);
;         Stage st;
;         if (more) load_tile<MODE != 1>(src, nkb * 64, tid, st);
.LBB0_2317:
	s_mul_i32 s0, s40, 0x8c00
	s_add_i32 s42, s0, 0
	v_add3_u32 v4, s42, v3, v230
	ds_read_b128 v[132:135], v4
	ds_read_b128 v[136:139], v4 offset:4352
	ds_read_b128 v[140:143], v4 offset:8704
	ds_read_b128 v[144:147], v4 offset:13056
	s_nop 0
	s_waitcnt lgkmcnt(3)
	v_mfma_f32_16x16x32_bf16 v[148:151], v[132:135], v[8:11], 0
	v_mfma_f32_16x16x32_bf16 v[132:135], v[132:135], v[24:27], 0
	s_waitcnt lgkmcnt(2)
	v_mfma_f32_16x16x32_bf16 v[152:155], v[136:139], v[8:11], 0
	v_mfma_f32_16x16x32_bf16 v[136:139], v[136:139], v[24:27], 0
	s_nop 0
	ds_read_b128 v[156:159], v4 offset:64
	ds_read_b128 v[160:163], v4 offset:4416
	s_nop 0
	s_waitcnt lgkmcnt(3)
	v_mfma_f32_16x16x32_bf16 v[234:237], v[140:143], v[8:11], 0
	v_mfma_f32_16x16x32_bf16 v[140:143], v[140:143], v[24:27], 0
	s_waitcnt lgkmcnt(2)
	v_mfma_f32_16x16x32_bf16 v[238:241], v[144:147], v[8:11], 0
	v_mfma_f32_16x16x32_bf16 v[144:147], v[144:147], v[24:27], 0
	s_nop 0
	ds_read_b128 v[242:245], v4 offset:8768
	ds_read_b128 v[246:249], v4 offset:13120
	s_nop 0
	s_waitcnt lgkmcnt(3)
	v_mfma_f32_16x16x32_bf16 v[148:151], v[156:159], v[12:15], v[148:151]
	v_mfma_f32_16x16x32_bf16 v[132:135], v[156:159], v[28:31], v[132:135]
	s_waitcnt lgkmcnt(2)
	v_mfma_f32_16x16x32_bf16 v[152:155], v[160:163], v[12:15], v[152:155]
	v_mfma_f32_16x16x32_bf16 v[136:139], v[160:163], v[28:31], v[136:139]
	s_nop 0
	ds_read_b128 v[156:159], v4 offset:128
	ds_read_b128 v[160:163], v4 offset:4480
	s_nop 0
	s_waitcnt lgkmcnt(3)
	v_mfma_f32_16x16x32_bf16 v[140:143], v[242:245], v[28:31], v[140:143]
	s_waitcnt lgkmcnt(2)
	v_mfma_f32_16x16x32_bf16 v[144:147], v[246:249], v[28:31], v[144:147]
	v_mfma_f32_16x16x32_bf16 v[234:237], v[242:245], v[12:15], v[234:237]
	v_mfma_f32_16x16x32_bf16 v[238:241], v[246:249], v[12:15], v[238:241]
	s_nop 0
	ds_read_b128 v[242:245], v4 offset:8832
	ds_read_b128 v[246:249], v4 offset:13184
	s_nop 0
	s_waitcnt lgkmcnt(3)
	v_mfma_f32_16x16x32_bf16 v[148:151], v[156:159], v[16:19], v[148:151]
	v_mfma_f32_16x16x32_bf16 v[132:135], v[156:159], v[32:35], v[132:135]
	s_waitcnt lgkmcnt(2)
	v_mfma_f32_16x16x32_bf16 v[152:155], v[160:163], v[16:19], v[152:155]
	v_mfma_f32_16x16x32_bf16 v[136:139], v[160:163], v[32:35], v[136:139]
	s_nop 0
	ds_read_b128 v[156:159], v4 offset:192
	ds_read_b128 v[160:163], v4 offset:4544
	s_nop 0
	s_waitcnt lgkmcnt(3)
	v_mfma_f32_16x16x32_bf16 v[234:237], v[242:245], v[16:19], v[234:237]
	v_mfma_f32_16x16x32_bf16 v[242:245], v[242:245], v[32:35], v[140:143]
	s_waitcnt lgkmcnt(2)
	v_mfma_f32_16x16x32_bf16 v[238:241], v[246:249], v[16:19], v[238:241]
	v_mfma_f32_16x16x32_bf16 v[246:249], v[246:249], v[32:35], v[144:147]
	s_nop 0
	ds_read_b128 v[166:169], v4 offset:8896
	ds_read_b128 v[218:221], v4 offset:13248
	s_nop 0
	s_waitcnt lgkmcnt(3)
	v_mfma_f32_16x16x32_bf16 v[148:151], v[156:159], v[20:23], v[148:151]
	v_mfma_f32_16x16x32_bf16 v[144:147], v[156:159], v[36:39], v[132:135]
	s_waitcnt lgkmcnt(2)
	v_mfma_f32_16x16x32_bf16 v[152:155], v[160:163], v[20:23], v[152:155]
	v_mfma_f32_16x16x32_bf16 v[140:143], v[160:163], v[36:39], v[136:139]
	s_nop 0
	s_nop 0
	s_waitcnt lgkmcnt(1)
	v_mfma_f32_16x16x32_bf16 v[156:159], v[166:169], v[20:23], v[234:237]
	v_mfma_f32_16x16x32_bf16 v[136:139], v[166:169], v[36:39], v[242:245]
	s_waitcnt lgkmcnt(0)
	v_mfma_f32_16x16x32_bf16 v[160:163], v[218:221], v[20:23], v[238:241]
	v_mfma_f32_16x16x32_bf16 v[132:135], v[218:221], v[36:39], v[246:249]
	s_nop 0
	s_cmp_eq_u32 s41, s37
	s_cselect_b64 s[0:1], -1, 0
	s_lshl_b64 s[6:7], 1, s41
	s_cmp_lg_u32 s41, s37
	v_and_b32_e32 v205, s7, v195
	v_and_b32_e32 v204, s6, v194
	s_cbranch_scc0 .LBB0_2320
	v_and_b32_e32 v7, v205, v197
	v_and_b32_e32 v6, v204, v196
	v_cmp_ne_u64_e32 vcc, 0, v[6:7]
	s_cmp_eq_u64 vcc, exec
	s_mov_b64 s[0:1], -1
	s_cbranch_scc0 .LBB0_2321
	v_max3_f32 v4, v148, s29, v149
	v_max3_f32 v4, v4, v150, v151
	v_max3_f32 v6, v144, s29, v145
	v_max3_f32 v6, v6, v146, v147
	v_max3_f32 v4, v4, v152, v153
	v_max3_f32 v4, v4, v154, v155
	v_max3_f32 v6, v6, v140, v141
	v_max3_f32 v6, v6, v142, v143
	v_max3_f32 v4, v4, v156, v157
	v_max3_f32 v4, v4, v158, v159
	v_max3_f32 v6, v6, v136, v137
	v_max3_f32 v7, v6, v138, v139
	v_max3_f32 v4, v4, v160, v161
	v_max3_f32 v6, v4, v162, v163
	v_max3_f32 v4, v7, v132, v133
	v_max3_f32 v7, v4, v134, v135
	s_mov_b64 s[0:1], 0
	s_branch .LBB0_2321

; #define LAS __attribute__((address_space(3)))
; __device__ __forceinline__ unsigned cvt_pk_bf16(float lo, float hi) { unsigned r; asm volatile("v_cvt_pk_bf16_f32 %0, %1, %2" : "=v"(r) : "v"(lo), "v"(hi)); return r; }
; template <int MODE, class MaskF> ...
;     ...
;         float ps = 0.f;
; #pragma unroll
;         for (int nt = 0; nt < 4; ++nt)
; #pragma unroll
;             for (int r = 0; r < 4; ++r) { float p = __builtin_amdgcn_exp2f(__builtin_fmaf(S[nt][mi][r], C2, -ref)); if constexpr (MODE == 2) p *= invl[mi]; S[nt][mi][r] = p; if constexpr (MODE == 1) ps += p; }
;         if constexpr (MODE == 1) l[mi] += ps;
;     }
;     if constexpr (MODE == 2) {
; #pragma unroll
;         for (int nt = 0; nt < 4; ++nt)
; #pragma unroll
;             for (int mi = 0; mi < 2; ++mi) { f32x4 v = S[nt][mi];
; #pragma unroll
;                 for (int r = 0; r < 4; ++r) { v[r] += __shfl_xor(v[r], 1); v[r] += __shfl_xor(v[r], 2); }
;                 if ((l15 & 3) == 0) *(LAS f32x4*)(PS + ((32 * wave + 16 * mi + l15) >> 2) * PS_STRIDE + 64 * kb + 16 * nt + 4 * lg) = v; }
;     }
;     if constexpr (MODE != 1) {
; #pragma unroll
;         for (int mi = 0; mi < 2; ++mi)
; #pragma unroll
;             for (int k2 = 0; k2 < 2; ++k2) { v4u w; w.x = pg8::cvt_pk_bf16(S[2 * k2][mi][0], S[2 * k2][mi][1]); w.y = pg8::cvt_pk_bf16(S[2 * k2][mi][2], S[2 * k2][mi][3]);
;                 w.z = pg8::cvt_pk_bf16(S[2 * k2 + 1][mi][0], S[2 * k2 + 1][mi][1]); w.w = pg8::cvt_pk_bf16(S[2 * k2 + 1][mi][2], S[2 * k2 + 1][mi][3]); Pf[mi][k2] = __builtin_bit_cast(bf16x8, w); }
; template <int MODE, class MaskF> ...
;     ...
;         if (more) load_tile<MODE != 1>(src, nkb * 64, tid, st);
.LBB0_2327:
	v_fma_f32 v140, v140, s30, -v193
	v_fma_f32 v132, v132, s30, -v193
	s_cmp_eq_u64 s[24:25], 0
	v_fma_f32 v7, v161, s30, -v191
	v_fma_f32 v131, v157, s30, -v191
	v_exp_f32_e32 v157, v140
	v_fma_f32 v140, v141, s30, -v193
	v_exp_f32_e32 v161, v132
	v_fma_f32 v132, v133, s30, -v193
	s_cselect_b64 s[0:1], -1, 0
	s_cmp_lg_u64 s[24:25], 0
	v_fma_f32 v128, v162, s30, -v191
	v_fma_f32 v130, v156, s30, -v191
	v_fma_f32 v156, v158, s30, -v191
	v_fma_f32 v144, v144, s30, -v193
	v_fma_f32 v145, v145, s30, -v193
	v_fma_f32 v146, v146, s30, -v193
	v_fma_f32 v147, v147, s30, -v193
	v_exp_f32_e32 v158, v140
	v_fma_f32 v140, v142, s30, -v193
	v_fma_f32 v136, v136, s30, -v193
	v_fma_f32 v137, v137, s30, -v193
	v_fma_f32 v138, v138, s30, -v193
	v_fma_f32 v139, v139, s30, -v193
	v_exp_f32_e32 v162, v132
	v_fma_f32 v132, v134, s30, -v193
	s_cselect_b64 s[6:7], -1, 0
	s_ff1_i32_b64 s41, s[24:25]
	v_fma_f32 v4, v163, s30, -v191
	v_fma_f32 v6, v160, s30, -v191
	v_fma_f32 v129, v159, s30, -v191
	v_fma_f32 v155, v155, s30, -v191
	v_fma_f32 v152, v152, s30, -v191
	v_fma_f32 v153, v153, s30, -v191
	v_fma_f32 v154, v154, s30, -v191
	v_fma_f32 v151, v151, s30, -v191
	v_fma_f32 v148, v148, s30, -v191
	v_fma_f32 v149, v149, s30, -v191
	v_fma_f32 v150, v150, s30, -v191
	v_exp_f32_e32 v144, v144
	v_exp_f32_e32 v145, v145
	v_exp_f32_e32 v146, v146
	v_exp_f32_e32 v147, v147
	v_exp_f32_e32 v159, v140
	v_fma_f32 v140, v143, s30, -v193
	v_exp_f32_e32 v136, v136
	v_exp_f32_e32 v137, v137
	v_exp_f32_e32 v138, v138
	v_exp_f32_e32 v139, v139
	v_exp_f32_e32 v163, v132
	v_fma_f32 v132, v135, s30, -v193
	v_exp_f32_e32 v4, v4
	v_exp_f32_e32 v6, v6
	v_exp_f32_e32 v7, v7
	v_exp_f32_e32 v128, v128
	v_exp_f32_e32 v129, v129
	v_exp_f32_e32 v130, v130
	v_exp_f32_e32 v131, v131
	v_exp_f32_e32 v156, v156
	v_exp_f32_e32 v155, v155
	v_exp_f32_e32 v152, v152
	v_exp_f32_e32 v153, v153
	v_exp_f32_e32 v154, v154
	v_exp_f32_e32 v151, v151
	v_exp_f32_e32 v148, v148
	v_exp_f32_e32 v149, v149
	v_exp_f32_e32 v150, v150
	v_exp_f32_e32 v160, v140
	v_exp_f32_e32 v166, v132
	v_cvt_pk_bf16_f32 v140, v148, v149
	v_cvt_pk_bf16_f32 v141, v150, v151
	v_cvt_pk_bf16_f32 v142, v152, v153
	v_cvt_pk_bf16_f32 v143, v154, v155
	v_cvt_pk_bf16_f32 v132, v130, v131
	v_cvt_pk_bf16_f32 v133, v156, v129
	v_cvt_pk_bf16_f32 v134, v6, v7
	v_cvt_pk_bf16_f32 v135, v128, v4
	v_cvt_pk_bf16_f32 v144, v144, v145
	v_cvt_pk_bf16_f32 v145, v146, v147
	v_cvt_pk_bf16_f32 v146, v157, v158
	v_cvt_pk_bf16_f32 v147, v159, v160
	v_cvt_pk_bf16_f32 v136, v136, v137
	v_cvt_pk_bf16_f32 v137, v138, v139
	v_cvt_pk_bf16_f32 v138, v161, v162
	v_cvt_pk_bf16_f32 v139, v163, v166
	s_and_b64 vcc, exec, s[0:1]
	s_cbranch_vccnz .LBB0_2329
	s_lshl_b32 s9, s41, 6
	v_or_b32_e32 v4, s9, v231
	v_lshlrev_b32_e32 v4, 8, v4
	v_lshl_add_u64 v[6:7], v[198:199], 0, v[4:5]
	s_lshl_b32 s18, s41, 7
	v_or_b32_e32 v4, s9, v211
	s_waitcnt vmcnt(2)
	v_lshl_add_u64 v[108:109], v[200:201], 0, s[18:19]
	v_lshlrev_b32_e32 v4, 8, v4
	global_load_dwordx4 v[112:115], v[6:7], off
	s_nop 0
	global_load_dwordx4 v[108:111], v[108:109], off
	v_lshl_add_u64 v[6:7], v[198:199], 0, v[4:5]
	s_waitcnt vmcnt(2)
	v_lshl_add_u64 v[116:117], v[202:203], 0, s[18:19]
	global_load_dwordx4 v[120:123], v[6:7], off
	s_nop 0
	global_load_dwordx4 v[116:119], v[116:117], off
; #define LAS __attribute__((address_space(3)))
; #define FA_LDV(slot_, g_) do { _Pragma("unroll") for (int q = 0; q < 2; ++q) { const int dt_ = ((g_) & 3) * 2 + q, k2_ = (g_) >> 2; \
;         va[slot_][q][0] = *(const LAS v2u*)(vbase + dt_ * 16 * VT_STRIDE + k2_ * 64); va[slot_][q][1] = *(const LAS v2u*)(vbase + dt_ * 16 * VT_STRIDE + k2_ * 64 + 32); } } while (0)
; __device__ __forceinline__ void tile_pv(const LAS unsigned char* buf, const bf16x8 (&Pf)[2][2], f32x4 (&O)[8][2], int l15, int lg, f32x4 (&OL)[2], bool with_l) {
;     if (with_l) { v4u ow; ow.x = ow.y = ow.z = ow.w = 0x3F803F80u; const bf16x8 ones = __builtin_bit_cast(bf16x8, ow);
; #pragma unroll
;         for (int k2 = 0; k2 < 2; ++k2)
; #pragma unroll
;             for (int mi = 0; mi < 2; ++mi) OL[mi] = __builtin_amdgcn_mfma_f32_16x16x32_bf16(ones, Pf[mi][k2], OL[mi], 0, 0, 0); }
;     const LAS unsigned char* vbase = buf + KS_BYTES + l15 * VT_STRIDE + lg * 8;
;     v2u va[2][2][2];
;     ...
;     FA_LDV(0, 0);
; #pragma unroll
;     for (int g = 0; g < 8; ++g) {
;         if (g < 7) FA_LDV((g + 1) & 1, g + 1);
;         __builtin_amdgcn_sched_barrier(0);
;         __builtin_amdgcn_s_setprio(1);
; #pragma unroll
;         for (int q = 0; q < 2; ++q) { const int dt = (g & 3) * 2 + q, k2 = g >> 2; v4u w; w.x = va[g & 1][q][0].x; w.y = va[g & 1][q][0].y; w.z = va[g & 1][q][1].x; w.w = va[g & 1][q][1].y; const bf16x8 vf = __builtin_bit_cast(bf16x8, w);
; #pragma unroll
;             for (int mi = 0; mi < 2; ++mi) O[dt][mi] = __builtin_amdgcn_mfma_f32_16x16x32_bf16(vf, Pf[mi][k2], O[dt][mi], 0, 0, 0); }
;         __builtin_amdgcn_s_setprio(0);
;         __builtin_amdgcn_sched_barrier(0);
;     }
; template <int MODE, class MaskF> ...
;     ...
;         if (more) store_tile<MODE != 1>(lds + (cur ^ 1) * BUF_BYTES, tid, st);
.LBB0_2329:
	s_mov_b32 s10, s8
	s_mov_b32 s11, s8
	s_mov_b32 s9, s8
	v_mov_b64_e32 v[150:151], s[10:11]
	v_mov_b64_e32 v[148:149], s[8:9]
	v_add3_u32 v4, s42, v173, v171
	v_add_u32_e32 v6, 0x4000, v4
	v_mfma_f32_16x16x32_bf16 v[124:127], v[148:151], v[140:143], v[124:127]
	v_add_u32_e32 v7, 0x4800, v4
	v_add_u32_e32 v160, 0x5000, v4
	v_add_u32_e32 v161, 0x5800, v4
	v_mfma_f32_16x16x32_bf16 v[104:107], v[148:151], v[144:147], v[104:107]
	ds_read2_b64 v[152:155], v160 offset0:192 offset1:196
	ds_read2_b64 v[156:159], v161 offset0:224 offset1:228
	v_mfma_f32_16x16x32_bf16 v[128:131], v[148:151], v[132:135], v[124:127]
	v_mfma_f32_16x16x32_bf16 v[104:107], v[148:151], v[136:139], v[104:107]
	s_nop 1
	ds_read2_b64 v[124:127], v6 offset0:128 offset1:132
	ds_read2_b64 v[148:151], v7 offset0:160 offset1:164
	s_nop 0
	s_waitcnt lgkmcnt(1)
	v_mfma_f32_16x16x32_bf16 v[100:103], v[124:127], v[140:143], v[100:103]
	v_mfma_f32_16x16x32_bf16 v[68:71], v[124:127], v[144:147], v[68:71]
	s_waitcnt lgkmcnt(0)
	v_mfma_f32_16x16x32_bf16 v[96:99], v[148:151], v[140:143], v[96:99]
	v_mfma_f32_16x16x32_bf16 v[64:67], v[148:151], v[144:147], v[64:67]
	s_nop 0
	v_add_u32_e32 v162, 0x6800, v4
	v_add_u32_e32 v163, 0x7000, v4
	ds_read2_b64 v[124:127], v162 offset1:4
	ds_read2_b64 v[148:151], v163 offset0:32 offset1:36
	s_nop 0
	v_mfma_f32_16x16x32_bf16 v[92:95], v[152:155], v[140:143], v[92:95]
	v_mfma_f32_16x16x32_bf16 v[60:63], v[152:155], v[144:147], v[60:63]
	v_mfma_f32_16x16x32_bf16 v[88:91], v[156:159], v[140:143], v[88:91]
	v_mfma_f32_16x16x32_bf16 v[56:59], v[156:159], v[144:147], v[56:59]
	s_nop 0
	v_add_u32_e32 v166, 0x7800, v4
	v_add_u32_e32 v4, 0x8000, v4
	ds_read2_b64 v[152:155], v166 offset0:64 offset1:68
	ds_read2_b64 v[156:159], v4 offset0:96 offset1:100
	s_nop 0
	s_waitcnt lgkmcnt(3)
	v_mfma_f32_16x16x32_bf16 v[84:87], v[124:127], v[140:143], v[84:87]
	v_mfma_f32_16x16x32_bf16 v[52:55], v[124:127], v[144:147], v[52:55]
	s_waitcnt lgkmcnt(2)
	v_mfma_f32_16x16x32_bf16 v[80:83], v[148:151], v[140:143], v[80:83]
	v_mfma_f32_16x16x32_bf16 v[48:51], v[148:151], v[144:147], v[48:51]
	s_nop 0
	ds_read2_b64 v[124:127], v6 offset0:136 offset1:140
	ds_read2_b64 v[148:151], v7 offset0:168 offset1:172
	s_nop 0
	s_waitcnt lgkmcnt(3)
	v_mfma_f32_16x16x32_bf16 v[76:79], v[152:155], v[140:143], v[76:79]
	v_mfma_f32_16x16x32_bf16 v[44:47], v[152:155], v[144:147], v[44:47]
	s_waitcnt lgkmcnt(2)
	v_mfma_f32_16x16x32_bf16 v[72:75], v[156:159], v[140:143], v[72:75]
	v_mfma_f32_16x16x32_bf16 v[40:43], v[156:159], v[144:147], v[40:43]
	s_nop 0
	ds_read2_b64 v[140:143], v160 offset0:200 offset1:204
	ds_read2_b64 v[144:147], v161 offset0:232 offset1:236
	s_nop 0
	s_waitcnt lgkmcnt(3)
	v_mfma_f32_16x16x32_bf16 v[100:103], v[124:127], v[132:135], v[100:103]
	v_mfma_f32_16x16x32_bf16 v[68:71], v[124:127], v[136:139], v[68:71]
	s_waitcnt lgkmcnt(2)
	v_mfma_f32_16x16x32_bf16 v[96:99], v[148:151], v[132:135], v[96:99]
	v_mfma_f32_16x16x32_bf16 v[64:67], v[148:151], v[136:139], v[64:67]
	s_nop 0
	ds_read2_b64 v[124:127], v162 offset0:8 offset1:12
	ds_read2_b64 v[148:151], v163 offset0:40 offset1:44
	s_nop 0
	s_waitcnt lgkmcnt(3)
	v_mfma_f32_16x16x32_bf16 v[92:95], v[140:143], v[132:135], v[92:95]
	v_mfma_f32_16x16x32_bf16 v[60:63], v[140:143], v[136:139], v[60:63]
	s_waitcnt lgkmcnt(2)
	v_mfma_f32_16x16x32_bf16 v[88:91], v[144:147], v[132:135], v[88:91]
	v_mfma_f32_16x16x32_bf16 v[56:59], v[144:147], v[136:139], v[56:59]
	s_nop 0
	ds_read2_b64 v[140:143], v166 offset0:72 offset1:76
	ds_read2_b64 v[144:147], v4 offset0:104 offset1:108
	s_nop 0
	s_waitcnt lgkmcnt(3)
	v_mfma_f32_16x16x32_bf16 v[84:87], v[124:127], v[132:135], v[84:87]
	v_mfma_f32_16x16x32_bf16 v[52:55], v[124:127], v[136:139], v[52:55]
	s_waitcnt lgkmcnt(2)
	v_mfma_f32_16x16x32_bf16 v[80:83], v[148:151], v[132:135], v[80:83]
	v_mfma_f32_16x16x32_bf16 v[48:51], v[148:151], v[136:139], v[48:51]
	s_nop 0
	s_nop 0
	s_waitcnt lgkmcnt(1)
	v_mfma_f32_16x16x32_bf16 v[76:79], v[140:143], v[132:135], v[76:79]
	v_mfma_f32_16x16x32_bf16 v[44:47], v[140:143], v[136:139], v[44:47]
	s_waitcnt lgkmcnt(0)
	v_mfma_f32_16x16x32_bf16 v[72:75], v[144:147], v[132:135], v[72:75]
	v_mfma_f32_16x16x32_bf16 v[40:43], v[144:147], v[136:139], v[40:43]
	s_nop 0
	s_andn2_b64 vcc, exec, s[6:7]
	s_xor_b32 s40, s40, 1
	s_cbranch_vccnz .LBB0_2331
	s_mul_i32 s6, s40, 0x8c00
	s_add_i32 s6, s6, 0
	v_add_u32_e32 v4, s6, v212
	v_add_u32_e32 v6, v4, v214
	v_add_u32_e32 v7, s6, v213
	v_add_u32_e32 v124, v7, v215
	v_add_u32_e32 v4, v4, v216
	v_add_u32_e32 v7, v7, v217
	s_waitcnt vmcnt(3)
	ds_write_b128 v6, v[112:115]
	s_waitcnt vmcnt(2)
	ds_write_b128 v124, v[108:111] offset:17408
	s_waitcnt vmcnt(1)
	ds_write_b128 v4, v[120:123]
	s_waitcnt vmcnt(0)
	ds_write_b128 v7, v[116:119] offset:17408

; #define LAS __attribute__((address_space(3)))
; template <int MODE, class MaskF> ...
;     ...
;     const LAS unsigned char* kbase = buf + l15 * KS_STRIDE + lg * 16;
;     bf16x8 kf[2][2];
; #pragma unroll
;     for (int q = 0; q < 2; ++q) kf[0][q] = *(const LAS bf16x8*)(kbase + q * 16 * KS_STRIDE);
; #pragma unroll
;     for (int h = 0; h < 8; ++h) { const int ks = h >> 1, n0 = (h & 1) * 2;
;         if (h < 7) { const int ks1 = (h + 1) >> 1, n1 = ((h + 1) & 1) * 2;
; #pragma unroll
;             for (int q = 0; q < 2; ++q) kf[(h + 1) & 1][q] = *(const LAS bf16x8*)(kbase + (n1 + q) * 16 * KS_STRIDE + ks1 * 64); }
;         __builtin_amdgcn_sched_barrier(0);
;         __builtin_amdgcn_s_setprio(1);
; #pragma unroll
;         for (int q = 0; q < 2; ++q)
; #pragma unroll
;             for (int mi = 0; mi < 2; ++mi) S[n0 + q][mi] = __builtin_amdgcn_mfma_f32_16x16x32_bf16(kf[h & 1][q], Qf[mi][ks], S[n0 + q][mi], 0, 0, 0);
;         __builtin_amdgcn_s_setprio(0);
;         __builtin_amdgcn_sched_barrier(0);
;     }
;     const float NEG = -__builtin_inff();
;     float mx[2] = {NEG, NEG};
;     if (mf.need(kb)) {
; #pragma unroll
;         for (int nt = 0; nt < 4; ++nt)
; #pragma unroll
;             for (int mi = 0; mi < 2; ++mi)
; #pragma unroll
;                 for (int r = 0; r < 4; ++r) { const float sv = mf.valid(kb, 16 * nt + 4 * lg + r, mi) ? S[nt][mi][r] : NEG; S[nt][mi][r] = sv; mx[mi] = fmaxf(mx[mi], sv); }
;     } else {
; #pragma unroll
;         for (int nt = 0; nt < 4; ++nt)
; #pragma unroll
;             for (int mi = 0; mi < 2; ++mi)
; #pragma unroll
;                 for (int r = 0; r < 4; ++r) mx[mi] = fmaxf(mx[mi], S[nt][mi][r]);
; template <int MODE, class MaskF> ...
;     ...
;         const bool more = tiles != 0ull; int nkb = 0;
;         if (more) { nkb = __builtin_ctzll(tiles); tiles &= tiles - 1ull; }
;         bf16x8 Pf[2][2];
;         tile_qk<MODE>(lds + cur * BUF_BYTES, Qf, O, m, l, invl, kb, mf, (LAS float*)(lds + PS_OFF), wave, l15, lg, Pf, OL);
;         __builtin_amdgcn_sched_barrier(0);
;         Stage st;
;         if (more) load_tile<MODE != 1>(src, nkb * 64, tid, st);
.LBB0_2337:
	s_mul_i32 s0, s25, 0x8c00
	s_add_i32 s39, s0, 0
	v_add3_u32 v4, s39, v3, v230
	ds_read_b128 v[132:135], v4
	ds_read_b128 v[136:139], v4 offset:4352
	ds_read_b128 v[140:143], v4 offset:8704
	ds_read_b128 v[144:147], v4 offset:13056
	s_nop 0
	s_waitcnt lgkmcnt(3)
	v_mfma_f32_16x16x32_bf16 v[148:151], v[132:135], v[8:11], 0
	v_mfma_f32_16x16x32_bf16 v[132:135], v[132:135], v[24:27], 0
	s_waitcnt lgkmcnt(2)
	v_mfma_f32_16x16x32_bf16 v[152:155], v[136:139], v[8:11], 0
	v_mfma_f32_16x16x32_bf16 v[136:139], v[136:139], v[24:27], 0
	s_nop 0
	ds_read_b128 v[156:159], v4 offset:64
	ds_read_b128 v[160:163], v4 offset:4416
	s_nop 0
	s_waitcnt lgkmcnt(3)
	v_mfma_f32_16x16x32_bf16 v[166:169], v[140:143], v[8:11], 0
	v_mfma_f32_16x16x32_bf16 v[140:143], v[140:143], v[24:27], 0
	s_waitcnt lgkmcnt(2)
	v_mfma_f32_16x16x32_bf16 v[218:221], v[144:147], v[8:11], 0
	v_mfma_f32_16x16x32_bf16 v[144:147], v[144:147], v[24:27], 0
	s_nop 0
	ds_read_b128 v[234:237], v4 offset:8768
	ds_read_b128 v[238:241], v4 offset:13120
	s_nop 0
	s_waitcnt lgkmcnt(3)
	v_mfma_f32_16x16x32_bf16 v[148:151], v[156:159], v[12:15], v[148:151]
	v_mfma_f32_16x16x32_bf16 v[132:135], v[156:159], v[28:31], v[132:135]
	s_waitcnt lgkmcnt(2)
	v_mfma_f32_16x16x32_bf16 v[152:155], v[160:163], v[12:15], v[152:155]
	v_mfma_f32_16x16x32_bf16 v[136:139], v[160:163], v[28:31], v[136:139]
	s_nop 0
	ds_read_b128 v[156:159], v4 offset:128
	ds_read_b128 v[160:163], v4 offset:4480
	s_nop 0
	s_waitcnt lgkmcnt(3)
	v_mfma_f32_16x16x32_bf16 v[140:143], v[234:237], v[28:31], v[140:143]
	s_waitcnt lgkmcnt(2)
	v_mfma_f32_16x16x32_bf16 v[144:147], v[238:241], v[28:31], v[144:147]
	v_mfma_f32_16x16x32_bf16 v[166:169], v[234:237], v[12:15], v[166:169]
	v_mfma_f32_16x16x32_bf16 v[218:221], v[238:241], v[12:15], v[218:221]
	s_nop 0
	ds_read_b128 v[234:237], v4 offset:8832
	ds_read_b128 v[238:241], v4 offset:13184
	s_nop 0
	s_waitcnt lgkmcnt(3)
	v_mfma_f32_16x16x32_bf16 v[148:151], v[156:159], v[16:19], v[148:151]
	v_mfma_f32_16x16x32_bf16 v[132:135], v[156:159], v[32:35], v[132:135]
	s_waitcnt lgkmcnt(2)
	v_mfma_f32_16x16x32_bf16 v[152:155], v[160:163], v[16:19], v[152:155]
	v_mfma_f32_16x16x32_bf16 v[136:139], v[160:163], v[32:35], v[136:139]
	s_nop 0
	ds_read_b128 v[156:159], v4 offset:192
	ds_read_b128 v[160:163], v4 offset:4544
	s_nop 0
	s_waitcnt lgkmcnt(3)
	v_mfma_f32_16x16x32_bf16 v[166:169], v[234:237], v[16:19], v[166:169]
	v_mfma_f32_16x16x32_bf16 v[234:237], v[234:237], v[32:35], v[140:143]
	s_waitcnt lgkmcnt(2)
	v_mfma_f32_16x16x32_bf16 v[218:221], v[238:241], v[16:19], v[218:221]
	v_mfma_f32_16x16x32_bf16 v[238:241], v[238:241], v[32:35], v[144:147]
	s_nop 0
	ds_read_b128 v[242:245], v4 offset:8896
	ds_read_b128 v[246:249], v4 offset:13248
	s_nop 0
	s_waitcnt lgkmcnt(3)
	v_mfma_f32_16x16x32_bf16 v[148:151], v[156:159], v[20:23], v[148:151]
	v_mfma_f32_16x16x32_bf16 v[144:147], v[156:159], v[36:39], v[132:135]
	s_waitcnt lgkmcnt(2)
	v_mfma_f32_16x16x32_bf16 v[152:155], v[160:163], v[20:23], v[152:155]
	v_mfma_f32_16x16x32_bf16 v[140:143], v[160:163], v[36:39], v[136:139]
	s_nop 0
	s_nop 0
	s_waitcnt lgkmcnt(1)
	v_mfma_f32_16x16x32_bf16 v[156:159], v[242:245], v[20:23], v[166:169]
	v_mfma_f32_16x16x32_bf16 v[136:139], v[242:245], v[36:39], v[234:237]
	s_waitcnt lgkmcnt(0)
	v_mfma_f32_16x16x32_bf16 v[160:163], v[246:249], v[20:23], v[218:221]
	v_mfma_f32_16x16x32_bf16 v[132:135], v[246:249], v[36:39], v[238:241]
	s_nop 0
	s_cmp_eq_u32 s38, s37
	s_cselect_b64 s[0:1], -1, 0
	s_cmp_le_i32 s38, s24
	s_cselect_b64 s[10:11], -1, 0
	s_or_b64 s[10:11], s[0:1], s[10:11]
	s_mov_b64 s[0:1], -1
	s_and_b64 vcc, exec, s[10:11]
	s_cbranch_vccnz .LBB0_2339
	v_max3_f32 v4, v148, s29, v149
	v_max3_f32 v4, v4, v150, v151
	v_max3_f32 v6, v144, s29, v145
	v_max3_f32 v6, v6, v146, v147
	v_max3_f32 v4, v4, v152, v153
	v_max3_f32 v4, v4, v154, v155
	v_max3_f32 v6, v6, v140, v141
	v_max3_f32 v6, v6, v142, v143
	v_max3_f32 v4, v4, v156, v157
	v_max3_f32 v4, v4, v158, v159
	v_max3_f32 v6, v6, v136, v137
	v_max3_f32 v7, v6, v138, v139
	v_max3_f32 v4, v4, v160, v161
	v_max3_f32 v6, v4, v162, v163
	v_max3_f32 v4, v7, v132, v133
	v_max3_f32 v7, v4, v134, v135
	s_mov_b64 s[0:1], 0

; #define LAS __attribute__((address_space(3)))
; __device__ __forceinline__ unsigned cvt_pk_bf16(float lo, float hi) { unsigned r; asm volatile("v_cvt_pk_bf16_f32 %0, %1, %2" : "=v"(r) : "v"(lo), "v"(hi)); return r; }
; template <int MODE, class MaskF> ...
;     ...
;         float ps = 0.f;
; #pragma unroll
;         for (int nt = 0; nt < 4; ++nt)
; #pragma unroll
;             for (int r = 0; r < 4; ++r) { float p = __builtin_amdgcn_exp2f(__builtin_fmaf(S[nt][mi][r], C2, -ref)); if constexpr (MODE == 2) p *= invl[mi]; S[nt][mi][r] = p; if constexpr (MODE == 1) ps += p; }
;         if constexpr (MODE == 1) l[mi] += ps;
;     }
;     if constexpr (MODE == 2) {
; #pragma unroll
;         for (int nt = 0; nt < 4; ++nt)
; #pragma unroll
;             for (int mi = 0; mi < 2; ++mi) { f32x4 v = S[nt][mi];
; #pragma unroll
;                 for (int r = 0; r < 4; ++r) { v[r] += __shfl_xor(v[r], 1); v[r] += __shfl_xor(v[r], 2); }
;                 if ((l15 & 3) == 0) *(LAS f32x4*)(PS + ((32 * wave + 16 * mi + l15) >> 2) * PS_STRIDE + 64 * kb + 16 * nt + 4 * lg) = v; }
;     }
;     if constexpr (MODE != 1) {
; #pragma unroll
;         for (int mi = 0; mi < 2; ++mi)
; #pragma unroll
;             for (int k2 = 0; k2 < 2; ++k2) { v4u w; w.x = pg8::cvt_pk_bf16(S[2 * k2][mi][0], S[2 * k2][mi][1]); w.y = pg8::cvt_pk_bf16(S[2 * k2][mi][2], S[2 * k2][mi][3]);
;                 w.z = pg8::cvt_pk_bf16(S[2 * k2 + 1][mi][0], S[2 * k2 + 1][mi][1]); w.w = pg8::cvt_pk_bf16(S[2 * k2 + 1][mi][2], S[2 * k2 + 1][mi][3]); Pf[mi][k2] = __builtin_bit_cast(bf16x8, w); }
; template <int MODE, class MaskF> ...
;     ...
;         if (more) load_tile<MODE != 1>(src, nkb * 64, tid, st);
.LBB0_2345:
	v_fma_f32 v140, v140, s30, -v202
	v_fma_f32 v132, v132, s30, -v202
	s_cmp_eq_u64 s[6:7], 0
	v_fma_f32 v7, v161, s30, -v201
	v_fma_f32 v131, v157, s30, -v201
	v_exp_f32_e32 v157, v140
	v_fma_f32 v140, v141, s30, -v202
	v_exp_f32_e32 v161, v132
	v_fma_f32 v132, v133, s30, -v202
	s_cselect_b64 s[0:1], -1, 0
	s_cmp_lg_u64 s[6:7], 0
	v_fma_f32 v128, v162, s30, -v201
	v_fma_f32 v130, v156, s30, -v201
	v_fma_f32 v156, v158, s30, -v201
	v_fma_f32 v144, v144, s30, -v202
	v_fma_f32 v145, v145, s30, -v202
	v_fma_f32 v146, v146, s30, -v202
	v_fma_f32 v147, v147, s30, -v202
	v_exp_f32_e32 v158, v140
	v_fma_f32 v140, v142, s30, -v202
	v_fma_f32 v136, v136, s30, -v202
	v_fma_f32 v137, v137, s30, -v202
	v_fma_f32 v138, v138, s30, -v202
	v_fma_f32 v139, v139, s30, -v202
	v_exp_f32_e32 v162, v132
	v_fma_f32 v132, v134, s30, -v202
	s_cselect_b64 s[22:23], -1, 0
	s_ff1_i32_b64 s38, s[6:7]
	v_fma_f32 v4, v163, s30, -v201
	v_fma_f32 v6, v160, s30, -v201
	v_fma_f32 v129, v159, s30, -v201
	v_fma_f32 v155, v155, s30, -v201
	v_fma_f32 v152, v152, s30, -v201
	v_fma_f32 v153, v153, s30, -v201
	v_fma_f32 v154, v154, s30, -v201
	v_fma_f32 v151, v151, s30, -v201
	v_fma_f32 v148, v148, s30, -v201
	v_fma_f32 v149, v149, s30, -v201
	v_fma_f32 v150, v150, s30, -v201
	v_exp_f32_e32 v144, v144
	v_exp_f32_e32 v145, v145
	v_exp_f32_e32 v146, v146
	v_exp_f32_e32 v147, v147
	v_exp_f32_e32 v159, v140
	v_fma_f32 v140, v143, s30, -v202
	v_exp_f32_e32 v136, v136
	v_exp_f32_e32 v137, v137
	v_exp_f32_e32 v138, v138
	v_exp_f32_e32 v139, v139
	v_exp_f32_e32 v163, v132
	v_fma_f32 v132, v135, s30, -v202
	v_exp_f32_e32 v4, v4
	v_exp_f32_e32 v6, v6
	v_exp_f32_e32 v7, v7
	v_exp_f32_e32 v128, v128
	v_exp_f32_e32 v129, v129
	v_exp_f32_e32 v130, v130
	v_exp_f32_e32 v131, v131
	v_exp_f32_e32 v156, v156
	v_exp_f32_e32 v155, v155
	v_exp_f32_e32 v152, v152
	v_exp_f32_e32 v153, v153
	v_exp_f32_e32 v154, v154
	v_exp_f32_e32 v151, v151
	v_exp_f32_e32 v148, v148
	v_exp_f32_e32 v149, v149
	v_exp_f32_e32 v150, v150
	v_exp_f32_e32 v160, v140
	v_exp_f32_e32 v166, v132
	v_cvt_pk_bf16_f32 v140, v148, v149
	v_cvt_pk_bf16_f32 v141, v150, v151
	v_cvt_pk_bf16_f32 v142, v152, v153
	v_cvt_pk_bf16_f32 v143, v154, v155
	v_cvt_pk_bf16_f32 v132, v130, v131
	v_cvt_pk_bf16_f32 v133, v156, v129
	v_cvt_pk_bf16_f32 v134, v6, v7
	v_cvt_pk_bf16_f32 v135, v128, v4
	v_cvt_pk_bf16_f32 v144, v144, v145
	v_cvt_pk_bf16_f32 v145, v146, v147
	v_cvt_pk_bf16_f32 v146, v157, v158
	v_cvt_pk_bf16_f32 v147, v159, v160
	v_cvt_pk_bf16_f32 v136, v136, v137
	v_cvt_pk_bf16_f32 v137, v138, v139
	v_cvt_pk_bf16_f32 v138, v161, v162
	v_cvt_pk_bf16_f32 v139, v163, v166
	s_and_b64 vcc, exec, s[0:1]
	s_cbranch_vccnz .LBB0_2347
	s_lshl_b32 s9, s38, 6
	v_or_b32_e32 v4, s9, v231
	v_lshlrev_b32_e32 v4, 8, v4
	v_lshl_add_u64 v[6:7], v[192:193], 0, v[4:5]
	s_lshl_b32 s18, s38, 7
	v_or_b32_e32 v4, s9, v211
	s_waitcnt vmcnt(2)
	v_lshl_add_u64 v[108:109], v[198:199], 0, s[18:19]
	v_lshlrev_b32_e32 v4, 8, v4
	global_load_dwordx4 v[112:115], v[6:7], off
	s_nop 0
	global_load_dwordx4 v[108:111], v[108:109], off
	v_lshl_add_u64 v[6:7], v[192:193], 0, v[4:5]
	s_waitcnt vmcnt(2)
	v_lshl_add_u64 v[116:117], v[190:191], 0, s[18:19]
	global_load_dwordx4 v[120:123], v[6:7], off
	s_nop 0
	global_load_dwordx4 v[116:119], v[116:117], off
; #define LAS __attribute__((address_space(3)))
; #define FA_LDV(slot_, g_) do { _Pragma("unroll") for (int q = 0; q < 2; ++q) { const int dt_ = ((g_) & 3) * 2 + q, k2_ = (g_) >> 2; \
;         va[slot_][q][0] = *(const LAS v2u*)(vbase + dt_ * 16 * VT_STRIDE + k2_ * 64); va[slot_][q][1] = *(const LAS v2u*)(vbase + dt_ * 16 * VT_STRIDE + k2_ * 64 + 32); } } while (0)
; __device__ __forceinline__ void tile_pv(const LAS unsigned char* buf, const bf16x8 (&Pf)[2][2], f32x4 (&O)[8][2], int l15, int lg, f32x4 (&OL)[2], bool with_l) {
;     if (with_l) { v4u ow; ow.x = ow.y = ow.z = ow.w = 0x3F803F80u; const bf16x8 ones = __builtin_bit_cast(bf16x8, ow);
; #pragma unroll
;         for (int k2 = 0; k2 < 2; ++k2)
; #pragma unroll
;             for (int mi = 0; mi < 2; ++mi) OL[mi] = __builtin_amdgcn_mfma_f32_16x16x32_bf16(ones, Pf[mi][k2], OL[mi], 0, 0, 0); }
;     const LAS unsigned char* vbase = buf + KS_BYTES + l15 * VT_STRIDE + lg * 8;
;     v2u va[2][2][2];
;     ...
;     FA_LDV(0, 0);
; #pragma unroll
;     for (int g = 0; g < 8; ++g) {
;         if (g < 7) FA_LDV((g + 1) & 1, g + 1);
;         __builtin_amdgcn_sched_barrier(0);
;         __builtin_amdgcn_s_setprio(1);
; #pragma unroll
;         for (int q = 0; q < 2; ++q) { const int dt = (g & 3) * 2 + q, k2 = g >> 2; v4u w; w.x = va[g & 1][q][0].x; w.y = va[g & 1][q][0].y; w.z = va[g & 1][q][1].x; w.w = va[g & 1][q][1].y; const bf16x8 vf = __builtin_bit_cast(bf16x8, w);
; #pragma unroll
;             for (int mi = 0; mi < 2; ++mi) O[dt][mi] = __builtin_amdgcn_mfma_f32_16x16x32_bf16(vf, Pf[mi][k2], O[dt][mi], 0, 0, 0); }
;         __builtin_amdgcn_s_setprio(0);
;         __builtin_amdgcn_sched_barrier(0);
;     }
; template <int MODE, class MaskF> ...
;     ...
;         if (more) store_tile<MODE != 1>(lds + (cur ^ 1) * BUF_BYTES, tid, st);
.LBB0_2347:
	s_mov_b32 s10, s8
	s_mov_b32 s11, s8
	s_mov_b32 s9, s8
	v_mov_b64_e32 v[150:151], s[10:11]
	v_mov_b64_e32 v[148:149], s[8:9]
	v_add3_u32 v4, s39, v173, v171
	v_add_u32_e32 v6, 0x4000, v4
	v_mfma_f32_16x16x32_bf16 v[124:127], v[148:151], v[140:143], v[124:127]
	v_add_u32_e32 v7, 0x4800, v4
	v_add_u32_e32 v160, 0x5000, v4
	v_add_u32_e32 v161, 0x5800, v4
	v_mfma_f32_16x16x32_bf16 v[104:107], v[148:151], v[144:147], v[104:107]
	ds_read2_b64 v[152:155], v160 offset0:192 offset1:196
	ds_read2_b64 v[156:159], v161 offset0:224 offset1:228
	v_mfma_f32_16x16x32_bf16 v[128:131], v[148:151], v[132:135], v[124:127]
	v_mfma_f32_16x16x32_bf16 v[104:107], v[148:151], v[136:139], v[104:107]
	s_nop 1
	ds_read2_b64 v[124:127], v6 offset0:128 offset1:132
	ds_read2_b64 v[148:151], v7 offset0:160 offset1:164
	s_nop 0
	s_waitcnt lgkmcnt(1)
	v_mfma_f32_16x16x32_bf16 v[100:103], v[124:127], v[140:143], v[100:103]
	v_mfma_f32_16x16x32_bf16 v[68:71], v[124:127], v[144:147], v[68:71]
	s_waitcnt lgkmcnt(0)
	v_mfma_f32_16x16x32_bf16 v[96:99], v[148:151], v[140:143], v[96:99]
	v_mfma_f32_16x16x32_bf16 v[64:67], v[148:151], v[144:147], v[64:67]
	s_nop 0
	v_add_u32_e32 v162, 0x6800, v4
	v_add_u32_e32 v163, 0x7000, v4
	ds_read2_b64 v[124:127], v162 offset1:4
	ds_read2_b64 v[148:151], v163 offset0:32 offset1:36
	s_nop 0
	v_mfma_f32_16x16x32_bf16 v[92:95], v[152:155], v[140:143], v[92:95]
	v_mfma_f32_16x16x32_bf16 v[60:63], v[152:155], v[144:147], v[60:63]
	v_mfma_f32_16x16x32_bf16 v[88:91], v[156:159], v[140:143], v[88:91]
	v_mfma_f32_16x16x32_bf16 v[56:59], v[156:159], v[144:147], v[56:59]
	s_nop 0
	v_add_u32_e32 v166, 0x7800, v4
	v_add_u32_e32 v4, 0x8000, v4
	ds_read2_b64 v[152:155], v166 offset0:64 offset1:68
	ds_read2_b64 v[156:159], v4 offset0:96 offset1:100
	s_nop 0
	s_waitcnt lgkmcnt(3)
	v_mfma_f32_16x16x32_bf16 v[84:87], v[124:127], v[140:143], v[84:87]
	v_mfma_f32_16x16x32_bf16 v[52:55], v[124:127], v[144:147], v[52:55]
	s_waitcnt lgkmcnt(2)
	v_mfma_f32_16x16x32_bf16 v[80:83], v[148:151], v[140:143], v[80:83]
	v_mfma_f32_16x16x32_bf16 v[48:51], v[148:151], v[144:147], v[48:51]
	s_nop 0
	ds_read2_b64 v[124:127], v6 offset0:136 offset1:140
	ds_read2_b64 v[148:151], v7 offset0:168 offset1:172
	s_nop 0
	s_waitcnt lgkmcnt(3)
	v_mfma_f32_16x16x32_bf16 v[76:79], v[152:155], v[140:143], v[76:79]
	v_mfma_f32_16x16x32_bf16 v[44:47], v[152:155], v[144:147], v[44:47]
	s_waitcnt lgkmcnt(2)
	v_mfma_f32_16x16x32_bf16 v[72:75], v[156:159], v[140:143], v[72:75]
	v_mfma_f32_16x16x32_bf16 v[40:43], v[156:159], v[144:147], v[40:43]
	s_nop 0
	ds_read2_b64 v[140:143], v160 offset0:200 offset1:204
	ds_read2_b64 v[144:147], v161 offset0:232 offset1:236
	s_nop 0
	s_waitcnt lgkmcnt(3)
	v_mfma_f32_16x16x32_bf16 v[100:103], v[124:127], v[132:135], v[100:103]
	v_mfma_f32_16x16x32_bf16 v[68:71], v[124:127], v[136:139], v[68:71]
	s_waitcnt lgkmcnt(2)
	v_mfma_f32_16x16x32_bf16 v[96:99], v[148:151], v[132:135], v[96:99]
	v_mfma_f32_16x16x32_bf16 v[64:67], v[148:151], v[136:139], v[64:67]
	s_nop 0
	ds_read2_b64 v[124:127], v162 offset0:8 offset1:12
	ds_read2_b64 v[148:151], v163 offset0:40 offset1:44
	s_nop 0
	s_waitcnt lgkmcnt(3)
	v_mfma_f32_16x16x32_bf16 v[92:95], v[140:143], v[132:135], v[92:95]
	v_mfma_f32_16x16x32_bf16 v[60:63], v[140:143], v[136:139], v[60:63]
	s_waitcnt lgkmcnt(2)
	v_mfma_f32_16x16x32_bf16 v[88:91], v[144:147], v[132:135], v[88:91]
	v_mfma_f32_16x16x32_bf16 v[56:59], v[144:147], v[136:139], v[56:59]
	s_nop 0
	ds_read2_b64 v[140:143], v166 offset0:72 offset1:76
	ds_read2_b64 v[144:147], v4 offset0:104 offset1:108
	s_nop 0
	s_waitcnt lgkmcnt(3)
	v_mfma_f32_16x16x32_bf16 v[84:87], v[124:127], v[132:135], v[84:87]
	v_mfma_f32_16x16x32_bf16 v[52:55], v[124:127], v[136:139], v[52:55]
	s_waitcnt lgkmcnt(2)
	v_mfma_f32_16x16x32_bf16 v[80:83], v[148:151], v[132:135], v[80:83]
	v_mfma_f32_16x16x32_bf16 v[48:51], v[148:151], v[136:139], v[48:51]
	s_nop 0
	s_nop 0
	s_waitcnt lgkmcnt(1)
	v_mfma_f32_16x16x32_bf16 v[76:79], v[140:143], v[132:135], v[76:79]
	v_mfma_f32_16x16x32_bf16 v[44:47], v[140:143], v[136:139], v[44:47]
	s_waitcnt lgkmcnt(0)
	v_mfma_f32_16x16x32_bf16 v[72:75], v[144:147], v[132:135], v[72:75]
	v_mfma_f32_16x16x32_bf16 v[40:43], v[144:147], v[136:139], v[40:43]
	s_nop 0
	s_andn2_b64 vcc, exec, s[22:23]
	s_xor_b32 s25, s25, 1
	s_cbranch_vccnz .LBB0_2349
	s_mul_i32 s9, s25, 0x8c00
	s_add_i32 s9, s9, 0
	v_add_u32_e32 v4, s9, v212
	v_add_u32_e32 v6, v4, v214
	v_add_u32_e32 v7, s9, v213
	v_add_u32_e32 v124, v7, v215
	v_add_u32_e32 v4, v4, v216
	v_add_u32_e32 v7, v7, v217
	s_waitcnt vmcnt(3)
	ds_write_b128 v6, v[112:115]
	s_waitcnt vmcnt(2)
	ds_write_b128 v124, v[108:111] offset:17408
	s_waitcnt vmcnt(1)
	ds_write_b128 v4, v[120:123]
	s_waitcnt vmcnt(0)
	ds_write_b128 v7, v[116:119] offset:17408

; #define SEAM(k) do { } while (0)
; #define SEAM(k) do { if (IN(k) && IN((k) + 1)) { xcd_barrier(bar); xcd_barrier(bar); } } while (0)
; #define SEAM(k) do { if (IN(k) && IN((k) + 1)) xcd_barrier(bar); } while (0)
; __device__ __forceinline__ void xcd_barrier(const XcdBarrier& b) {
;     asm volatile("s_waitcnt vmcnt(0)" ::: "memory");
;     __syncthreads();
;     if (threadIdx.x == 0) {
;         unsigned* bar = b.bar;
;         __builtin_amdgcn_s_waitcnt(0);
;         unsigned nloc = b.st[0], nx = b.st[1];
;         if (nloc == 0u) { xcd_barrier_complete(bar, b.x, nloc, nx); b.st[0] = nloc; b.st[1] = nx; }
; template <int L>
; __device__ __forceinline__ void layer_body(const Ctx& c, const Args& args, const XcdBarrier& bar, int lo, int hi) {
;     ...
;         if constexpr (L == 1) SEAM(P0 + 5);
.LBB0_2352:
	s_setprio 0
	v_readlane_b32 s0, v253, 13
	v_readlane_b32 s1, v253, 14
	s_cmp_gt_i32 s1, 22
	s_cselect_b64 s[0:1], -1, 0
	s_and_b64 s[6:7], s[12:13], s[0:1]
	s_andn2_b64 vcc, exec, s[6:7]
	s_cbranch_vccnz .LBB0_2406
	s_waitcnt vmcnt(0)
	s_waitcnt vmcnt(0) lgkmcnt(0)
	s_barrier
	s_mov_b64 s[6:7], exec
	v_readlane_b32 s8, v253, 50
	v_readlane_b32 s9, v253, 51
	s_and_b64 s[8:9], s[6:7], s[8:9]
	s_mov_b64 exec, s[8:9]
	s_cbranch_execz .LBB0_2405
	s_add_i32 s8, 0, 0x26f20
	v_mov_b32_e32 v3, s8
	s_waitcnt vmcnt(0) expcnt(0) lgkmcnt(0)
	ds_read_b32 v5, v3
	s_add_i32 s8, 0, 0x26f24
	v_mov_b32_e32 v3, s8
	ds_read_b32 v4, v3
	s_waitcnt lgkmcnt(1)
	v_cmp_ne_u32_e32 vcc, 0, v5
	s_cbranch_vccnz .LBB0_2369
	v_readlane_b32 s8, v253, 10
	v_readlane_b32 s9, v253, 11
	s_load_dwordx2 s[12:13], s[8:9], 0x4
	v_readlane_b32 s42, v253, 0
	v_readlane_b32 s43, v253, 1
	s_add_u32 s8, s42, 0x4200
	s_addc_u32 s9, s43, 0
	s_add_u32 s10, s42, 0x4400
	s_addc_u32 s11, s43, 0
	s_waitcnt lgkmcnt(0)
	s_mul_i32 s50, s12, s33
	s_add_u32 s12, s42, 0x4500
	s_mul_i32 s50, s50, s13
	s_addc_u32 s13, s43, 0
	s_add_u32 s14, s42, 0x4600
	s_addc_u32 s15, s43, 0
	s_add_u32 s16, s42, 0x4700
	s_addc_u32 s17, s43, 0
	s_add_u32 s18, s42, 0x4800
	s_addc_u32 s19, s43, 0
	s_add_u32 s20, s42, 0x4900
	s_addc_u32 s21, s43, 0
	s_add_u32 s22, s42, 0x4a00
	s_addc_u32 s23, s43, 0
	s_add_u32 s24, s42, 0x4b00
	s_addc_u32 s25, s43, 0
	s_add_u32 s26, s42, 0x4c00
	s_addc_u32 s27, s43, 0
	s_add_u32 s28, s42, 0x4d00
	s_addc_u32 s29, s43, 0
	s_add_u32 s30, s42, 0x4e00
	s_addc_u32 s31, s43, 0
	s_add_u32 s34, s42, 0x4f00
	s_addc_u32 s35, s43, 0
	s_add_u32 s36, s42, 0x5000
	s_addc_u32 s37, s43, 0
	s_add_u32 s38, s42, 0x5100
	s_addc_u32 s39, s43, 0
	s_add_u32 s40, s42, 0x5200
	s_addc_u32 s41, s43, 0
	s_add_u32 s42, s42, 0x5300
	s_addc_u32 s43, s43, 0
	s_mov_b32 s51, 1
	v_mov_b32_e32 v19, 0
	s_branch .LBB0_2357

; __global__ void __launch_bounds__(512, 2) mega_fwd(Args args) {
	.amdhsa_kernel _Z8mega_fwd4Args
		.amdhsa_group_segment_fixed_size 0
		.amdhsa_private_segment_fixed_size 0
		.amdhsa_kernarg_size 560
		.amdhsa_user_sgpr_count 2
		.amdhsa_user_sgpr_dispatch_ptr 0
		.amdhsa_user_sgpr_queue_ptr 0
		.amdhsa_user_sgpr_kernarg_segment_ptr 1
		.amdhsa_user_sgpr_dispatch_id 0
		.amdhsa_user_sgpr_kernarg_preload_length 0
		.amdhsa_user_sgpr_kernarg_preload_offset 0
		.amdhsa_user_sgpr_private_segment_size 0
		.amdhsa_uses_dynamic_stack 0
		.amdhsa_enable_private_segment 0
		.amdhsa_system_sgpr_workgroup_id_x 1
		.amdhsa_system_sgpr_workgroup_id_y 0
		.amdhsa_system_sgpr_workgroup_id_z 0
		.amdhsa_system_sgpr_workgroup_info 0
		.amdhsa_system_vgpr_workitem_id 0
		.amdhsa_next_free_vgpr 256
		.amdhsa_next_free_sgpr 98
		.amdhsa_accum_offset 256
		.amdhsa_reserve_vcc 1
		.amdhsa_float_round_mode_32 0
		.amdhsa_float_round_mode_16_64 0
		.amdhsa_float_denorm_mode_32 3
		.amdhsa_float_denorm_mode_16_64 3
		.amdhsa_dx10_clamp 1
		.amdhsa_ieee_mode 1
		.amdhsa_fp16_overflow 0
		.amdhsa_tg_split 0
		.amdhsa_exception_fp_ieee_invalid_op 0
		.amdhsa_exception_fp_denorm_src 0
		.amdhsa_exception_fp_ieee_div_zero 0
		.amdhsa_exception_fp_ieee_overflow 0
		.amdhsa_exception_fp_ieee_underflow 0
		.amdhsa_exception_fp_ieee_inexact 0
		.amdhsa_exception_int_div_zero 0
	.end_amdhsa_kernel

; __global__ void __launch_bounds__(512, 2) mega_fwd(Args args) {
amdhsa.kernels:
  - .agpr_count:     0
    .args:
      - .offset:         0
        .size:           304
        .value_kind:     by_value
      - .offset:         304
        .size:           4
        .value_kind:     hidden_block_count_x
      - .offset:         308
        .size:           4
        .value_kind:     hidden_block_count_y
      - .offset:         312
        .size:           4
        .value_kind:     hidden_block_count_z
      - .offset:         316
        .size:           2
        .value_kind:     hidden_group_size_x
      - .offset:         318
        .size:           2
        .value_kind:     hidden_group_size_y
      - .offset:         320
        .size:           2
        .value_kind:     hidden_group_size_z
      - .offset:         322
        .size:           2
        .value_kind:     hidden_remainder_x
      - .offset:         324
        .size:           2
        .value_kind:     hidden_remainder_y
      - .offset:         326
        .size:           2
        .value_kind:     hidden_remainder_z
      - .offset:         344
        .size:           8
        .value_kind:     hidden_global_offset_x
      - .offset:         352
        .size:           8
        .value_kind:     hidden_global_offset_y
      - .offset:         360
        .size:           8
        .value_kind:     hidden_global_offset_z
      - .offset:         368
        .size:           2
        .value_kind:     hidden_grid_dims
      - .offset:         424
        .size:           4
        .value_kind:     hidden_dynamic_lds_size
    .group_segment_fixed_size: 0
    .kernarg_segment_align: 8
    .kernarg_segment_size: 560
    .language:       OpenCL C
    .language_version:
      - 2
      - 0
    .max_flat_workgroup_size: 512
    .name:           _Z8mega_fwd4Args
    .private_segment_fixed_size: 0
    .sgpr_count:     104
    .sgpr_spill_count: 166
    .symbol:         _Z8mega_fwd4Args.kd
    .uniform_work_group_size: 1
    .uses_dynamic_stack: false
    .vgpr_count:     256
    .vgpr_spill_count: 0
    .wavefront_size: 64
